# P2 short-conv loop: xor-16 butterfly step via v_permlane16_swap instead of ds_swizzle (3 regular chains)
# speedup vs baseline: 1.0050x; 1.0005x over previous
.LBB0_270:
	v_or_b32_e32 v124, s8, v164
	v_med3_i32 v26, v124, 0, v197
	v_max_i32_e32 v27, -4, v124
	v_ashrrev_i32_e32 v125, 31, v124
	v_mov_b64_e32 v[24:25], s[72:73]
	v_or_b32_e32 v30, s38, v26
	v_add_u32_e32 v34, 4, v27
	v_lshl_add_u64 v[26:27], s[38:39], 0, v[124:125]
	v_add_u32_e32 v28, -1, v124
	v_or_b32_e32 v128, 1, v124
	v_mad_u64_u32 v[24:25], s[10:11], v26, s28, v[24:25]
	v_or_b32_e32 v126, 2, v124
	v_or_b32_e32 v122, 3, v124
	v_med3_i32 v29, v28, 0, v197
	v_med3_i32 v31, v128, 0, v197
	v_min_u32_e32 v40, 0xfff, v34
	v_mad_i32_i24 v25, v27, s28, v25
	v_med3_i32 v32, v126, 0, v197
	v_med3_i32 v33, v122, 0, v197
	v_cmp_gt_u32_e32 vcc, s46, v28
	v_or_b32_e32 v35, s38, v29
	v_mad_u64_u32 v[28:29], s[10:11], v30, s28, v[70:71]
	v_or_b32_e32 v36, s38, v31
	v_lshlrev_b64 v[30:31], 11, v[26:27]
	v_or_b32_e32 v26, s38, v40
	v_lshl_add_u64 v[24:25], v[24:25], 0, v[178:179]
	v_cndmask_b32_e64 v64, 0, 1.0, vcc
	v_or_b32_e32 v37, s38, v32
	v_or_b32_e32 v38, s38, v33
	v_lshl_add_u64 v[146:147], v[72:73], 0, v[30:31]
	v_mad_u64_u32 v[30:31], s[10:11], v26, s28, v[70:71]
	v_add_co_u32_e32 v26, vcc, s46, v24
	v_mad_u64_u32 v[32:33], s[10:11], v35, s28, v[70:71]
	v_mad_i32_i24 v29, s39, v187, v29
	v_mad_u64_u32 v[34:35], s[10:11], v36, s28, v[70:71]
	v_mad_u64_u32 v[36:37], s[10:11], v37, s28, v[70:71]
	v_mad_u64_u32 v[38:39], s[10:11], v38, s28, v[70:71]
	v_addc_co_u32_e32 v27, vcc, 0, v25, vcc
	global_load_dwordx4 v[130:133], v[28:29], off offset:2560
	v_mad_i32_i24 v33, s39, v187, v33
	v_mad_i32_i24 v35, s39, v187, v35
	v_mad_i32_i24 v37, s39, v187, v37
	v_mad_i32_i24 v39, s39, v187, v39
	global_load_dwordx4 v[134:137], v[28:29], off offset:3584
	global_load_dwordx4 v[138:141], v[34:35], off offset:2560
	global_load_dwordx4 v[142:145], v[32:33], off offset:2560
	global_load_dwordx4 v[148:151], v[34:35], off offset:3584
	global_load_dwordx4 v[152:155], v[32:33], off offset:3584
	global_load_dwordx4 v[156:159], v[36:37], off offset:3584
	global_load_dwordx4 v[160:163], v[36:37], off offset:2560
	global_load_dwordx4 v[48:51], v[38:39], off offset:3584
	global_load_dwordx4 v[166:169], v[24:25], off offset:1536
	v_add_co_u32_e32 v28, vcc, s54, v24
	v_mad_i32_i24 v31, s39, v187, v31
	s_nop 0
	v_addc_co_u32_e32 v29, vcc, 0, v25, vcc
	v_add_co_u32_e32 v36, vcc, s55, v24
	s_mov_b32 s8, 4
	s_nop 0
	v_addc_co_u32_e32 v37, vcc, 0, v25, vcc
	v_add_co_u32_e32 v174, vcc, s64, v24
	s_waitcnt vmcnt(8)
	v_lshlrev_b32_e32 v200, 16, v135
	v_addc_co_u32_e32 v175, vcc, 0, v25, vcc
	v_add_co_u32_e32 v180, vcc, s65, v24
	s_waitcnt vmcnt(7)
	v_lshlrev_b32_e32 v211, 16, v138
	v_addc_co_u32_e32 v181, vcc, 0, v25, vcc
	global_load_dwordx4 v[52:55], v[38:39], off offset:2560
	global_load_dwordx4 v[32:35], v[30:31], off offset:3584
	global_load_dwordx4 v[170:173], v[26:27], off offset:1536
	global_load_dwordx4 v[56:59], v[28:29], off offset:-4096
	global_load_dwordx4 v[60:63], v[28:29], off
	global_load_dwordx4 v[40:43], v[28:29], off offset:2560
	global_load_dwordx4 v[44:47], v[36:37], off offset:2560
	s_nop 0
	global_load_dwordx4 v[24:27], v[174:175], off offset:1024
	global_load_dwordx4 v[36:39], v[30:31], off offset:2560
	s_nop 0
	global_load_dwordx4 v[28:31], v[180:181], off offset:1024
	s_waitcnt vmcnt(16)
	v_lshlrev_b32_e32 v210, 16, v142
	s_waitcnt vmcnt(15)
	v_lshlrev_b32_e32 v213, 16, v148
	s_waitcnt vmcnt(14)
	v_lshlrev_b32_e32 v212, 16, v152
	v_and_b32_e32 v215, 0xffff0000, v138
	v_and_b32_e32 v214, 0xffff0000, v142
	v_and_b32_e32 v217, 0xffff0000, v148
	v_and_b32_e32 v216, 0xffff0000, v152
	v_lshlrev_b32_e32 v219, 16, v139
	v_lshlrev_b32_e32 v218, 16, v143
	v_lshlrev_b32_e32 v221, 16, v149
	v_lshlrev_b32_e32 v220, 16, v153
	v_and_b32_e32 v139, 0xffff0000, v139
	v_and_b32_e32 v138, 0xffff0000, v143
	v_and_b32_e32 v143, 0xffff0000, v149
	v_and_b32_e32 v142, 0xffff0000, v153
	v_lshlrev_b32_e32 v149, 16, v140
	v_lshlrev_b32_e32 v148, 16, v144
	v_lshlrev_b32_e32 v153, 16, v150
	v_lshlrev_b32_e32 v152, 16, v154
	v_and_b32_e32 v223, 0xffff0000, v140
	v_and_b32_e32 v222, 0xffff0000, v144
	v_and_b32_e32 v225, 0xffff0000, v150
	v_and_b32_e32 v224, 0xffff0000, v154
	v_lshlrev_b32_e32 v227, 16, v141
	v_lshlrev_b32_e32 v226, 16, v145
	v_lshlrev_b32_e32 v229, 16, v151
	v_lshlrev_b32_e32 v228, 16, v155
	v_and_b32_e32 v141, 0xffff0000, v141
	v_and_b32_e32 v140, 0xffff0000, v145
	v_and_b32_e32 v145, 0xffff0000, v151
	v_and_b32_e32 v144, 0xffff0000, v155
	v_and_b32_e32 v202, 0xffff0000, v135
	s_waitcnt vmcnt(13)
	v_lshlrev_b32_e32 v193, 16, v156
	v_and_b32_e32 v135, 0xffff0000, v156
	v_lshlrev_b32_e32 v201, 16, v157
	v_and_b32_e32 v203, 0xffff0000, v157
	v_pk_mul_f32 v[150:151], v[210:211], v[212:213]
	v_pk_mul_f32 v[154:155], v[214:215], v[216:217]
	v_pk_mul_f32 v[156:157], v[218:219], v[220:221]
	v_pk_mul_f32 v[138:139], v[138:139], v[142:143]
	v_pk_mul_f32 v[142:143], v[148:149], v[152:153]
	v_pk_mul_f32 v[148:149], v[222:223], v[224:225]
	v_pk_mul_f32 v[210:211], v[226:227], v[228:229]
	v_pk_mul_f32 v[140:141], v[140:141], v[144:145]
	v_lshlrev_b32_e32 v180, 16, v131
	v_and_b32_e32 v182, 0xffff0000, v131
	v_lshlrev_b32_e32 v188, 16, v133
	v_and_b32_e32 v190, 0xffff0000, v133
	v_lshlrev_b32_e32 v206, 16, v137
	v_and_b32_e32 v208, 0xffff0000, v137
	s_waitcnt vmcnt(12)
	v_lshlrev_b32_e32 v175, 16, v160
	v_and_b32_e32 v131, 0xffff0000, v160
	v_lshlrev_b32_e32 v181, 16, v161
	v_and_b32_e32 v183, 0xffff0000, v161
	v_lshlrev_b32_e32 v185, 16, v162
	v_lshlrev_b32_e32 v205, 16, v158
	v_and_b32_e32 v133, 0xffff0000, v162
	v_and_b32_e32 v137, 0xffff0000, v158
	v_lshlrev_b32_e32 v189, 16, v163
	v_lshlrev_b32_e32 v207, 16, v159
	v_and_b32_e32 v191, 0xffff0000, v163
	v_and_b32_e32 v209, 0xffff0000, v159
	v_pk_mul_f32 v[162:163], v[64:65], v[150:151]
	v_pk_mul_f32 v[160:161], v[64:65], v[154:155]
	v_pk_mul_f32 v[158:159], v[64:65], v[156:157]
	v_pk_mul_f32 v[156:157], v[64:65], v[138:139]
	v_pk_mul_f32 v[154:155], v[64:65], v[142:143]
	v_pk_mul_f32 v[152:153], v[64:65], v[148:149]
	v_pk_mul_f32 v[150:151], v[64:65], v[210:211]
	v_pk_mul_f32 v[148:149], v[64:65], v[140:141]
	v_lshlrev_b32_e32 v174, 16, v130
	v_and_b32_e32 v130, 0xffff0000, v130
	s_waitcnt vmcnt(7)
	v_lshlrev_b32_e32 v230, 16, v170
	v_and_b32_e32 v232, 0xffff0000, v170
	v_mul_f32_e32 v64, 0xbfb8aa3b, v230
	v_lshlrev_b32_e32 v234, 16, v171
	v_mul_f32_e32 v67, 0xbfb8aa3b, v232
	v_exp_f32_e32 v64, v64
	v_lshlrev_b32_e32 v192, 16, v134
	v_and_b32_e32 v134, 0xffff0000, v134
	v_lshlrev_b32_e32 v231, 16, v166
	v_and_b32_e32 v233, 0xffff0000, v166
	v_and_b32_e32 v166, 0xffff0000, v171
	v_mul_f32_e32 v123, 0xbfb8aa3b, v234
	v_exp_f32_e32 v67, v67
	v_lshlrev_b32_e32 v236, 16, v172
	v_pk_mul_f32 v[144:145], v[192:193], v[174:175]
	v_pk_mul_f32 v[130:131], v[134:135], v[130:131]
	v_pk_mul_f32 v[134:135], v[200:201], v[180:181]
	v_pk_mul_f32 v[170:171], v[202:203], v[182:183]
	v_pk_mul_f32 v[180:181], v[208:209], v[190:191]
	v_mul_f32_e32 v125, 0xbfb8aa3b, v166
	v_exp_f32_e32 v123, v123
	v_lshlrev_b32_e32 v184, 16, v132
	v_lshlrev_b32_e32 v204, 16, v136
	v_and_b32_e32 v238, 0xffff0000, v172
	v_mul_f32_e32 v127, 0xbfb8aa3b, v236
	v_pk_mul_f32 v[144:145], v[68:69], v[144:145]
	v_pk_mul_f32 v[142:143], v[68:69], v[130:131]
	v_pk_mul_f32 v[138:139], v[68:69], v[170:171]
	v_pk_mul_f32 v[130:131], v[68:69], v[180:181]
	v_pk_mul_f32 v[170:171], v[86:87], v[162:163]
	v_pk_mul_f32 v[190:191], v[76:77], v[148:149]
	v_exp_f32_e32 v125, v125
	v_and_b32_e32 v132, 0xffff0000, v132
	v_and_b32_e32 v136, 0xffff0000, v136
	v_lshlrev_b32_e32 v237, 16, v168
	v_and_b32_e32 v239, 0xffff0000, v168
	v_lshlrev_b32_e32 v240, 16, v173
	v_and_b32_e32 v168, 0xffff0000, v173
	v_pk_mul_f32 v[172:173], v[204:205], v[184:185]
	v_mul_f32_e32 v129, 0xbfb8aa3b, v238
	v_exp_f32_e32 v127, v127
	v_pk_mul_f32 v[192:193], v[86:87], v[144:145]
	v_fma_f32 v144, v20, v144, v170
	v_fma_f32 v170, v19, v130, v190
	v_add_f32_e32 v64, 1.0, v64
	v_pk_mul_f32 v[132:133], v[136:137], v[132:133]
	v_pk_mul_f32 v[174:175], v[206:207], v[188:189]
	v_mul_f32_e32 v165, 0xbfb8aa3b, v240
	v_pk_mul_f32 v[136:137], v[68:69], v[172:173]
	v_pk_mul_f32 v[172:173], v[88:89], v[160:161]
	v_exp_f32_e32 v129, v129
	v_add_f32_e32 v191, v170, v191
	v_add_f32_e32 v67, 1.0, v67
	v_rcp_f32_e32 v170, v64
	v_mul_f32_e32 v186, 0xbfb8aa3b, v168
	v_pk_mul_f32 v[140:141], v[68:69], v[134:135]
	v_pk_mul_f32 v[134:135], v[68:69], v[132:133]
	v_pk_mul_f32 v[132:133], v[68:69], v[174:175]
	v_pk_mul_f32 v[174:175], v[82:83], v[158:159]
	v_exp_f32_e32 v148, v165
	v_pk_mul_f32 v[200:201], v[88:89], v[142:143]
	v_fma_f32 v142, v21, v142, v172
	v_add_f32_e32 v123, 1.0, v123
	v_rcp_f32_e32 v172, v67
	v_pk_mul_f32 v[180:181], v[84:85], v[156:157]
	v_pk_mul_f32 v[188:189], v[74:75], v[150:151]
	v_exp_f32_e32 v150, v186
	v_pk_mul_f32 v[202:203], v[82:83], v[140:141]
	v_fma_f32 v140, v22, v140, v174
	v_add_f32_e32 v125, 1.0, v125
	v_rcp_f32_e32 v174, v123
	v_pk_mul_f32 v[182:183], v[78:79], v[154:155]
	v_pk_mul_f32 v[204:205], v[84:85], v[138:139]
	v_fma_f32 v138, v23, v138, v180
	v_add_f32_e32 v171, v144, v171
	v_add_f32_e32 v127, 1.0, v127
	v_rcp_f32_e32 v180, v125
	v_pk_mul_f32 v[184:185], v[80:81], v[152:153]
	v_pk_mul_f32 v[206:207], v[78:79], v[136:137]
	v_pk_mul_f32 v[210:211], v[74:75], v[132:133]
	v_fma_f32 v136, v16, v136, v182
	v_fma_f32 v132, v18, v132, v188
	v_add_f32_e32 v173, v142, v173
	v_add_f32_e32 v129, 1.0, v129
	v_rcp_f32_e32 v182, v127
	v_pk_mul_f32 v[170:171], v[170:171], v[230:231]
	v_lshlrev_b32_e32 v235, 16, v167
	v_pk_mul_f32 v[208:209], v[80:81], v[134:135]
	v_fma_f32 v134, v17, v134, v184
	v_add_f32_e32 v175, v140, v175
	v_add_f32_e32 v189, v132, v189
	v_add_f32_e32 v132, 1.0, v148
	v_rcp_f32_e32 v184, v129
	v_pk_mul_f32 v[172:173], v[172:173], v[232:233]
	v_mul_f32_e32 v64, v171, v171
	v_and_b32_e32 v167, 0xffff0000, v167
	v_add_f32_e32 v181, v138, v181
	v_add_f32_e32 v185, v134, v185
	v_add_f32_e32 v134, 1.0, v150
	v_rcp_f32_e32 v188, v132
	v_pk_mul_f32 v[174:175], v[174:175], v[234:235]
	v_fmac_f32_e32 v64, v173, v173
	v_add_f32_e32 v183, v136, v183
	v_rcp_f32_e32 v190, v134
	v_pk_mul_f32 v[166:167], v[180:181], v[166:167]
	v_fmac_f32_e32 v64, v175, v175
	v_pk_mul_f32 v[180:181], v[182:183], v[236:237]
	v_fmac_f32_e32 v64, v167, v167
	v_lshlrev_b32_e32 v241, 16, v169
	v_pk_mul_f32 v[182:183], v[184:185], v[238:239]
	v_fmac_f32_e32 v64, v181, v181
	v_and_b32_e32 v169, 0xffff0000, v169
	v_pk_mul_f32 v[184:185], v[188:189], v[240:241]
	v_fmac_f32_e32 v64, v183, v183
	v_pk_mul_f32 v[168:169], v[190:191], v[168:169]
	v_fmac_f32_e32 v64, v185, v185
	v_fmac_f32_e32 v64, v169, v169
	v_fma_f32 v152, v20, v163, v192
	v_fma_f32 v154, v21, v161, v200
	v_fma_f32 v156, v22, v159, v202
	v_fma_f32 v158, v23, v157, v204
	v_add_f32_dpp v64, v64, v64 quad_perm:[1,0,3,2] row_mask:0xf bank_mask:0xf
	v_fma_f32 v160, v16, v155, v206
	v_fma_f32 v162, v17, v153, v208
	v_fma_f32 v165, v18, v151, v210
	v_add_f32_e32 v193, v152, v193
	v_add_f32_dpp v64, v64, v64 quad_perm:[2,3,0,1] row_mask:0xf bank_mask:0xf
	v_add_f32_e32 v201, v154, v201
	v_add_f32_e32 v203, v156, v203
	v_add_f32_e32 v205, v158, v205
	v_add_f32_e32 v207, v160, v207
	v_add_f32_dpp v64, v64, v64 row_half_mirror row_mask:0xf bank_mask:0xf
	v_add_f32_e32 v209, v162, v209
	v_add_f32_e32 v211, v165, v211
	v_add_f32_dpp v64, v64, v64 row_mirror row_mask:0xf bank_mask:0xf
	v_mov_b32_e32 v67, v64
	s_nop 1
	v_permlane16_swap_b32_e32 v64, v67
	v_add_f32_e32 v64, v64, v67
	v_mov_b32_e32 v67, v64
	s_nop 1
	v_permlane32_swap_b32_e32 v64, v67
	v_add_f32_e32 v64, v64, v67
	v_fmamk_f32 v64, v64, 0x3b000000, v196
	v_mul_f32_e32 v67, 0x4b800000, v64
	v_cmp_gt_f32_e32 vcc, s35, v64
	s_nop 1
	v_cndmask_b32_e32 v64, v64, v67, vcc
	v_rsq_f32_e32 v64, v64
	s_nop 0
	v_mul_f32_e32 v67, 0x45800000, v64
	v_cndmask_b32_e32 v64, v64, v67, vcc
	v_mul_f32_e32 v67, v171, v64
	v_mul_f32_e32 v123, v173, v64
	v_mul_f32_e32 v125, v175, v64
	v_mul_f32_e32 v127, v167, v64
	v_mul_f32_e32 v129, v181, v64
	v_mul_f32_e32 v132, v183, v64
	v_mul_f32_e32 v134, v185, v64
	v_mul_f32_e32 v64, v169, v64
	v_mul_f32_e32 v67, v170, v67
	v_mul_f32_e32 v123, v172, v123
	v_mul_f32_e32 v125, v174, v125
	v_mul_f32_e32 v127, v166, v127
	v_mul_f32_e32 v129, v180, v129
	v_mul_f32_e32 v132, v182, v132
	v_mul_f32_e32 v134, v184, v134
	v_mul_f32_e32 v64, v168, v64
	v_cvt_pk_bf16_f32 v166, v67, v123
	v_cvt_pk_bf16_f32 v167, v125, v127
	v_cvt_pk_bf16_f32 v168, v129, v132
	v_cvt_pk_bf16_f32 v169, v134, v64
	global_store_dwordx4 v[146:147], v[166:169], off offset:1024
	v_pk_mul_f32 v[146:147], v[76:77], v[130:131]
	s_waitcnt vmcnt(6)
	v_and_b32_e32 v166, 0xffff0000, v60
	v_fma_f32 v64, v19, v149, v146
	v_lshlrev_b32_e32 v146, 16, v60
	v_mul_f32_e32 v60, 0xbfb8aa3b, v166
	v_exp_f32_e32 v60, v60
	v_mul_f32_e32 v67, 0xbfb8aa3b, v146
	v_exp_f32_e32 v67, v67
	v_add_f32_e32 v169, v64, v147
	v_add_f32_e32 v60, 1.0, v60
	v_rcp_f32_e32 v200, v60
	v_lshlrev_b32_e32 v60, 16, v61
	v_add_f32_e32 v64, 1.0, v67
	v_lshlrev_b32_e32 v147, 16, v56
	v_and_b32_e32 v167, 0xffff0000, v56
	v_mul_f32_e32 v56, 0xbfb8aa3b, v60
	v_rcp_f32_e32 v192, v64
	v_exp_f32_e32 v64, v56
	v_and_b32_e32 v56, 0xffff0000, v61
	v_mul_f32_e32 v61, 0xbfb8aa3b, v56
	v_exp_f32_e32 v67, v61
	v_add_f32_e32 v64, 1.0, v64
	v_rcp_f32_e32 v202, v64
	v_lshlrev_b32_e32 v170, 16, v62
	v_add_f32_e32 v64, 1.0, v67
	v_rcp_f32_e32 v204, v64
	v_mul_f32_e32 v64, 0xbfb8aa3b, v170
	v_exp_f32_e32 v64, v64
	v_lshlrev_b32_e32 v61, 16, v57
	v_and_b32_e32 v57, 0xffff0000, v57
	v_pk_mul_f32 v[172:173], v[204:205], v[56:57]
	v_add_f32_e32 v56, 1.0, v64
	v_rcp_f32_e32 v206, v56
	v_and_b32_e32 v56, 0xffff0000, v62
	v_mul_f32_e32 v57, 0xbfb8aa3b, v56
	v_exp_f32_e32 v62, v57
	v_lshlrev_b32_e32 v171, 16, v58
	v_and_b32_e32 v57, 0xffff0000, v58
	v_pk_mul_f32 v[146:147], v[192:193], v[146:147]
	v_add_f32_e32 v58, 1.0, v62
	v_lshlrev_b32_e32 v62, 16, v63
	v_rcp_f32_e32 v208, v58
	v_mul_f32_e32 v58, 0xbfb8aa3b, v62
	v_exp_f32_e32 v64, v58
	v_and_b32_e32 v58, 0xffff0000, v63
	v_mul_f32_e32 v63, 0xbfb8aa3b, v58
	v_exp_f32_e32 v63, v63
	v_pk_mul_f32 v[174:175], v[208:209], v[56:57]
	v_add_f32_e32 v56, 1.0, v64
	v_rcp_f32_e32 v210, v56
	v_add_f32_e32 v56, 1.0, v63
	v_pk_mul_f32 v[166:167], v[200:201], v[166:167]
	v_rcp_f32_e32 v168, v56
	v_mul_f32_e32 v56, v147, v147
	v_pk_mul_f32 v[60:61], v[202:203], v[60:61]
	v_fmac_f32_e32 v56, v167, v167
	v_fmac_f32_e32 v56, v61, v61
	v_pk_mul_f32 v[170:171], v[206:207], v[170:171]
	v_fmac_f32_e32 v56, v173, v173
	v_lshlrev_b32_e32 v63, 16, v59
	v_fmac_f32_e32 v56, v171, v171
	v_pk_mul_f32 v[62:63], v[210:211], v[62:63]
	v_and_b32_e32 v59, 0xffff0000, v59
	v_fmac_f32_e32 v56, v175, v175
	v_pk_mul_f32 v[168:169], v[168:169], v[58:59]
	v_fmac_f32_e32 v56, v63, v63
	v_fmac_f32_e32 v56, v169, v169
	v_ashrrev_i32_e32 v129, 31, v128
	s_nop 0
	v_add_f32_dpp v56, v56, v56 quad_perm:[1,0,3,2] row_mask:0xf bank_mask:0xf
	s_nop 1
	v_add_f32_dpp v56, v56, v56 quad_perm:[2,3,0,1] row_mask:0xf bank_mask:0xf
	s_nop 1
	v_add_f32_dpp v56, v56, v56 row_half_mirror row_mask:0xf bank_mask:0xf
	s_nop 1
	v_add_f32_dpp v56, v56, v56 row_mirror row_mask:0xf bank_mask:0xf
	v_mov_b32_e32 v57, v56
	s_nop 1
	v_permlane16_swap_b32_e32 v56, v57
	v_add_f32_e32 v56, v56, v57
	v_mov_b32_e32 v57, v56
	s_nop 1
	v_permlane32_swap_b32_e32 v56, v57
	v_add_f32_e32 v56, v56, v57
	v_fmamk_f32 v56, v56, 0x3b000000, v196
	v_mul_f32_e32 v57, 0x4b800000, v56
	v_cmp_gt_f32_e32 vcc, s35, v56
	s_nop 1
	v_cndmask_b32_e32 v56, v56, v57, vcc
	v_rsq_f32_e32 v56, v56
	s_nop 0
	v_mul_f32_e32 v57, 0x45800000, v56
	v_cndmask_b32_e32 v59, v56, v57, vcc
	v_mul_f32_e32 v56, v147, v59
	v_mul_f32_e32 v57, v167, v59
	v_mul_f32_e32 v56, v146, v56
	v_mul_f32_e32 v57, v166, v57
	v_cvt_pk_bf16_f32 v56, v56, v57
	v_mul_f32_e32 v57, v61, v59
	v_mul_f32_e32 v58, v173, v59
	v_mul_f32_e32 v57, v60, v57
	v_mul_f32_e32 v58, v172, v58
	v_cvt_pk_bf16_f32 v57, v57, v58
	v_mul_f32_e32 v58, v171, v59
	v_mul_f32_e32 v60, v175, v59
	v_mul_f32_e32 v58, v170, v58
	v_mul_f32_e32 v60, v174, v60
	v_cvt_pk_bf16_f32 v58, v58, v60
	v_mul_f32_e32 v60, v63, v59
	v_mul_f32_e32 v59, v169, v59
	v_mul_f32_e32 v60, v62, v60
	v_mul_f32_e32 v59, v168, v59
	v_cvt_pk_bf16_f32 v59, v60, v59
	v_lshl_add_u64 v[60:61], s[38:39], 0, v[128:129]
	v_lshlrev_b64 v[60:61], 11, v[60:61]
	v_lshl_add_u64 v[60:61], v[72:73], 0, v[60:61]
	global_store_dwordx4 v[60:61], v[56:59], off offset:1024
	s_waitcnt vmcnt(5)
	v_and_b32_e32 v184, 0xffff0000, v44
	v_lshlrev_b32_e32 v182, 16, v44
	v_mul_f32_e32 v44, 0xbfb8aa3b, v184
	v_exp_f32_e32 v44, v44
	v_mov_b32_e32 v142, v161
	v_pk_mul_f32 v[160:161], v[104:105], v[142:143]
	v_lshlrev_b32_e32 v183, 16, v40
	v_and_b32_e32 v185, 0xffff0000, v40
	v_add_f32_e32 v40, 1.0, v44
	v_lshlrev_b32_e32 v188, 16, v45
	v_add_f32_e32 v161, v160, v161
	v_rcp_f32_e32 v160, v40
	v_mul_f32_e32 v40, 0xbfb8aa3b, v188
	v_exp_f32_e32 v44, v40
	v_and_b32_e32 v40, 0xffff0000, v45
	v_mul_f32_e32 v45, 0xbfb8aa3b, v40
	v_lshlrev_b32_e32 v60, 16, v49
	v_and_b32_e32 v128, 0xffff0000, v49
	v_mul_f32_e32 v49, 0xbfb8aa3b, v182
	v_exp_f32_e32 v45, v45
	v_exp_f32_e32 v49, v49
	v_mov_b32_e32 v140, v159
	v_pk_mul_f32 v[166:167], v[98:99], v[140:141]
	v_mov_b32_e32 v138, v157
	v_add_f32_e32 v44, 1.0, v44
	v_mov_b32_e32 v144, v163
	v_add_f32_e32 v167, v166, v167
	v_pk_mul_f32 v[168:169], v[100:101], v[138:139]
	v_rcp_f32_e32 v166, v44
	v_add_f32_e32 v44, 1.0, v45
	v_pk_mul_f32 v[162:163], v[102:103], v[144:145]
	v_add_f32_e32 v169, v168, v169
	v_add_f32_e32 v49, 1.0, v49
	v_rcp_f32_e32 v168, v44
	v_lshlrev_b32_e32 v44, 16, v46
	v_and_b32_e32 v190, 0xffff0000, v46
	v_add_f32_e32 v163, v162, v163
	v_rcp_f32_e32 v162, v49
	v_mul_f32_e32 v49, 0xbfb8aa3b, v44
	v_mul_f32_e32 v46, 0xbfb8aa3b, v190
	v_exp_f32_e32 v49, v49
	v_exp_f32_e32 v46, v46
	v_mov_b32_e32 v136, v155
	v_mov_b32_e32 v134, v153
	v_pk_mul_f32 v[170:171], v[94:95], v[136:137]
	v_pk_mul_f32 v[172:173], v[96:97], v[134:135]
	v_lshlrev_b32_e32 v45, 16, v42
	v_add_f32_e32 v49, 1.0, v49
	v_and_b32_e32 v191, 0xffff0000, v42
	v_add_f32_e32 v42, 1.0, v46
	v_lshlrev_b32_e32 v192, 16, v47
	v_add_f32_e32 v171, v170, v171
	v_add_f32_e32 v173, v172, v173
	v_rcp_f32_e32 v170, v49
	v_rcp_f32_e32 v172, v42
	v_mul_f32_e32 v42, 0xbfb8aa3b, v192
	v_add_u32_e32 v49, 4, v124
	v_lshlrev_b32_e32 v56, 16, v48
	v_lshlrev_b32_e32 v58, 16, v52
	v_exp_f32_e32 v46, v42
	v_and_b32_e32 v42, 0xffff0000, v47
	v_cmp_gt_u32_e32 vcc, s46, v49
	s_waitcnt vmcnt(3)
	v_lshlrev_b32_e32 v59, 16, v36
	v_lshlrev_b32_e32 v57, 16, v32
	v_and_b32_e32 v48, 0xffff0000, v48
	v_and_b32_e32 v52, 0xffff0000, v52
	v_lshlrev_b32_e32 v62, 16, v53
	v_and_b32_e32 v146, 0xffff0000, v53
	v_mul_f32_e32 v47, 0xbfb8aa3b, v42
	v_cndmask_b32_e64 v67, 0, 1.0, vcc
	v_and_b32_e32 v53, 0xffff0000, v36
	v_and_b32_e32 v49, 0xffff0000, v32
	v_lshlrev_b32_e32 v61, 16, v33
	v_and_b32_e32 v129, 0xffff0000, v33
	v_pk_mul_f32 v[32:33], v[56:57], v[58:59]
	v_exp_f32_e32 v47, v47
	v_lshlrev_b32_e32 v63, 16, v37
	v_and_b32_e32 v147, 0xffff0000, v37
	v_pk_mul_f32 v[32:33], v[66:67], v[32:33]
	v_pk_mul_f32 v[36:37], v[48:49], v[52:53]
	v_fmac_f32_e32 v163, v12, v32
	v_pk_mul_f32 v[36:37], v[66:67], v[36:37]
	v_pk_mul_f32 v[48:49], v[60:61], v[62:63]
	v_lshlrev_b32_e32 v148, 16, v50
	v_lshlrev_b32_e32 v150, 16, v54
	v_lshlrev_b32_e32 v152, 16, v51
	v_and_b32_e32 v156, 0xffff0000, v51
	v_mov_b32_e32 v132, v151
	v_mov_b32_e32 v130, v149
	v_lshlrev_b32_e32 v151, 16, v38
	v_lshlrev_b32_e32 v149, 16, v34
	v_and_b32_e32 v51, 0xffff0000, v34
	v_lshlrev_b32_e32 v153, 16, v35
	v_and_b32_e32 v157, 0xffff0000, v35
	v_pk_mul_f32 v[34:35], v[162:163], v[182:183]
	v_fmac_f32_e32 v161, v13, v36
	v_pk_mul_f32 v[48:49], v[66:67], v[48:49]
	v_pk_mul_f32 v[56:57], v[128:129], v[146:147]
	v_and_b32_e32 v50, 0xffff0000, v50
	v_and_b32_e32 v54, 0xffff0000, v54
	v_lshlrev_b32_e32 v154, 16, v55
	v_and_b32_e32 v158, 0xffff0000, v55
	v_pk_mul_f32 v[174:175], v[90:91], v[132:133]
	v_lshlrev_b32_e32 v189, 16, v41
	v_add_f32_e32 v46, 1.0, v46
	v_and_b32_e32 v55, 0xffff0000, v38
	v_lshlrev_b32_e32 v155, 16, v39
	v_and_b32_e32 v159, 0xffff0000, v39
	v_pk_mul_f32 v[38:39], v[160:161], v[184:185]
	v_fmac_f32_e32 v167, v14, v48
	v_pk_mul_f32 v[56:57], v[66:67], v[56:57]
	v_pk_mul_f32 v[58:59], v[148:149], v[150:151]
	v_mul_f32_e32 v64, v35, v35
	v_add_f32_e32 v175, v174, v175
	v_pk_mul_f32 v[180:181], v[92:93], v[130:131]
	v_and_b32_e32 v41, 0xffff0000, v41
	v_rcp_f32_e32 v174, v46
	v_add_f32_e32 v46, 1.0, v47
	v_pk_mul_f32 v[52:53], v[166:167], v[188:189]
	v_fmac_f32_e32 v169, v15, v56
	v_pk_mul_f32 v[58:59], v[66:67], v[58:59]
	v_pk_mul_f32 v[50:51], v[50:51], v[54:55]
	v_fmac_f32_e32 v64, v39, v39
	v_add_f32_e32 v181, v180, v181
	v_rcp_f32_e32 v180, v46
	v_pk_mul_f32 v[40:41], v[168:169], v[40:41]
	v_fmac_f32_e32 v171, v4, v58
	v_pk_mul_f32 v[50:51], v[66:67], v[50:51]
	v_pk_mul_f32 v[60:61], v[152:153], v[154:155]
	v_fmac_f32_e32 v64, v53, v53
	v_pk_mul_f32 v[44:45], v[170:171], v[44:45]
	v_fmac_f32_e32 v173, v5, v50
	v_pk_mul_f32 v[60:61], v[66:67], v[60:61]
	v_pk_mul_f32 v[124:125], v[156:157], v[158:159]
	v_fmac_f32_e32 v64, v41, v41
	v_lshlrev_b32_e32 v193, 16, v43
	v_pk_mul_f32 v[54:55], v[172:173], v[190:191]
	v_fmac_f32_e32 v175, v6, v60
	v_pk_mul_f32 v[124:125], v[66:67], v[124:125]
	v_fmac_f32_e32 v64, v45, v45
	v_and_b32_e32 v43, 0xffff0000, v43
	v_pk_mul_f32 v[62:63], v[174:175], v[192:193]
	v_fmac_f32_e32 v181, v7, v124
	v_fmac_f32_e32 v64, v55, v55
	v_pk_mul_f32 v[42:43], v[180:181], v[42:43]
	v_fmac_f32_e32 v64, v63, v63
	v_fmac_f32_e32 v64, v43, v43
	v_pk_mul_f32 v[32:33], v[118:119], v[32:33]
	v_ashrrev_i32_e32 v127, 31, v126
	v_fma_f32 v32, v8, v145, v32
	v_lshl_add_u64 v[46:47], s[38:39], 0, v[126:127]
	v_add_f32_dpp v64, v64, v64 quad_perm:[1,0,3,2] row_mask:0xf bank_mask:0xf
	v_add_f32_e32 v127, v32, v33
	v_pk_mul_f32 v[32:33], v[120:121], v[36:37]
	v_lshlrev_b64 v[46:47], 11, v[46:47]
	v_fma_f32 v32, v9, v143, v32
	v_add_f32_dpp v36, v64, v64 quad_perm:[2,3,0,1] row_mask:0xf bank_mask:0xf
	v_add_f32_e32 v37, v32, v33
	v_pk_mul_f32 v[32:33], v[114:115], v[48:49]
	v_lshl_add_u64 v[46:47], v[72:73], 0, v[46:47]
	v_fma_f32 v32, v10, v141, v32
	v_add_f32_dpp v36, v36, v36 row_half_mirror row_mask:0xf bank_mask:0xf
	v_add_f32_e32 v49, v32, v33
	v_pk_mul_f32 v[32:33], v[116:117], v[56:57]
	v_add_f32_dpp v36, v36, v36 row_mirror row_mask:0xf bank_mask:0xf
	v_fma_f32 v32, v11, v139, v32
	ds_swizzle_b32 v48, v36 offset:swizzle(SWAP,16)
	v_add_f32_e32 v57, v32, v33
	v_pk_mul_f32 v[32:33], v[110:111], v[58:59]
	s_nop 0
	v_fma_f32 v32, v0, v137, v32
	v_add_f32_e32 v59, v32, v33
	v_pk_mul_f32 v[32:33], v[112:113], v[50:51]
	s_nop 0
	v_fma_f32 v32, v1, v135, v32
	v_add_f32_e32 v51, v32, v33
	s_waitcnt lgkmcnt(0)
	v_add_f32_e32 v32, v36, v48
	v_mov_b32_e32 v33, v32
	s_nop 1
	v_permlane32_swap_b32_e32 v32, v33
	v_add_f32_e32 v32, v32, v33
	v_fmamk_f32 v32, v32, 0x3b000000, v196
	v_mul_f32_e32 v33, 0x4b800000, v32
	v_cmp_gt_f32_e32 vcc, s35, v32
	s_nop 1
	v_cndmask_b32_e32 v32, v32, v33, vcc
	v_rsq_f32_e32 v36, v32
	v_pk_mul_f32 v[32:33], v[106:107], v[60:61]
	s_nop 0
	v_fma_f32 v32, v2, v133, v32
	v_add_f32_e32 v61, v32, v33
	v_mul_f32_e32 v32, 0x45800000, v36
	v_cndmask_b32_e32 v36, v36, v32, vcc
	v_mul_f32_e32 v32, v35, v36
	v_mul_f32_e32 v33, v39, v36
	v_mul_f32_e32 v32, v34, v32
	v_mul_f32_e32 v33, v38, v33
	v_cvt_pk_bf16_f32 v32, v32, v33
	v_mul_f32_e32 v33, v53, v36
	v_mul_f32_e32 v34, v41, v36
	v_mul_f32_e32 v33, v52, v33
	v_mul_f32_e32 v34, v40, v34
	v_cvt_pk_bf16_f32 v33, v33, v34
	v_mul_f32_e32 v34, v45, v36
	v_mul_f32_e32 v35, v55, v36
	v_mul_f32_e32 v34, v44, v34
	v_mul_f32_e32 v35, v54, v35
	v_cvt_pk_bf16_f32 v34, v34, v35
	v_mul_f32_e32 v35, v63, v36
	v_mul_f32_e32 v35, v62, v35
	v_mul_f32_e32 v36, v43, v36
	v_mul_f32_e32 v36, v42, v36
	v_cvt_pk_bf16_f32 v35, v35, v36
	global_store_dwordx4 v[46:47], v[32:35], off offset:1024
	s_nop 1
	v_pk_mul_f32 v[32:33], v[108:109], v[124:125]
	v_ashrrev_i32_e32 v123, 31, v122
	v_fma_f32 v35, v3, v131, v32
	s_waitcnt vmcnt(3)
	v_lshlrev_b32_e32 v32, 16, v28
	v_mul_f32_e32 v34, 0xbfb8aa3b, v32
	v_exp_f32_e32 v36, v34
	v_and_b32_e32 v34, 0xffff0000, v28
	v_mul_f32_e32 v28, 0xbfb8aa3b, v34
	v_exp_f32_e32 v28, v28
	v_add_f32_e32 v39, v35, v33
	v_add_f32_e32 v33, 1.0, v36
	v_rcp_f32_e32 v126, v33
	v_add_f32_e32 v28, 1.0, v28
	v_rcp_f32_e32 v36, v28
	v_lshlrev_b32_e32 v28, 16, v29
	v_lshlrev_b32_e32 v33, 16, v24
	v_and_b32_e32 v35, 0xffff0000, v24
	v_mul_f32_e32 v24, 0xbfb8aa3b, v28
	v_pk_mul_f32 v[34:35], v[36:37], v[34:35]
	v_exp_f32_e32 v36, v24
	v_and_b32_e32 v24, 0xffff0000, v29
	v_mul_f32_e32 v29, 0xbfb8aa3b, v24
	v_exp_f32_e32 v37, v29
	v_add_f32_e32 v36, 1.0, v36
	v_rcp_f32_e32 v48, v36
	v_lshlrev_b32_e32 v29, 16, v25
	v_add_f32_e32 v36, 1.0, v37
	v_rcp_f32_e32 v56, v36
	v_lshlrev_b32_e32 v36, 16, v30
	v_mul_f32_e32 v37, 0xbfb8aa3b, v36
	v_exp_f32_e32 v37, v37
	v_and_b32_e32 v25, 0xffff0000, v25
	v_pk_mul_f32 v[40:41], v[56:57], v[24:25]
	v_pk_mul_f32 v[32:33], v[126:127], v[32:33]
	v_add_f32_e32 v24, 1.0, v37
	v_rcp_f32_e32 v58, v24
	v_and_b32_e32 v24, 0xffff0000, v30
	v_mul_f32_e32 v25, 0xbfb8aa3b, v24
	v_exp_f32_e32 v30, v25
	v_lshlrev_b32_e32 v37, 16, v26
	v_and_b32_e32 v25, 0xffff0000, v26
	v_pk_mul_f32 v[28:29], v[48:49], v[28:29]
	v_add_f32_e32 v26, 1.0, v30
	v_lshlrev_b32_e32 v30, 16, v31
	v_rcp_f32_e32 v50, v26
	v_mul_f32_e32 v26, 0xbfb8aa3b, v30
	v_exp_f32_e32 v38, v26
	v_and_b32_e32 v26, 0xffff0000, v31
	v_mul_f32_e32 v31, 0xbfb8aa3b, v26
	v_exp_f32_e32 v31, v31
	v_pk_mul_f32 v[42:43], v[50:51], v[24:25]
	v_add_f32_e32 v24, 1.0, v38
	v_rcp_f32_e32 v60, v24
	v_add_f32_e32 v24, 1.0, v31
	v_rcp_f32_e32 v38, v24
	v_mul_f32_e32 v24, v33, v33
	v_fmac_f32_e32 v24, v35, v35
	v_fmac_f32_e32 v24, v29, v29
	v_pk_mul_f32 v[36:37], v[58:59], v[36:37]
	v_fmac_f32_e32 v24, v41, v41
	v_lshlrev_b32_e32 v31, 16, v27
	v_fmac_f32_e32 v24, v37, v37
	v_pk_mul_f32 v[30:31], v[60:61], v[30:31]
	v_and_b32_e32 v27, 0xffff0000, v27
	v_fmac_f32_e32 v24, v43, v43
	v_pk_mul_f32 v[38:39], v[38:39], v[26:27]
	v_fmac_f32_e32 v24, v31, v31
	v_fmac_f32_e32 v24, v39, v39
	s_nop 1
	v_add_f32_dpp v24, v24, v24 quad_perm:[1,0,3,2] row_mask:0xf bank_mask:0xf
	s_nop 1
	v_add_f32_dpp v24, v24, v24 quad_perm:[2,3,0,1] row_mask:0xf bank_mask:0xf
	s_nop 1
	v_add_f32_dpp v24, v24, v24 row_half_mirror row_mask:0xf bank_mask:0xf
	s_nop 1
	v_add_f32_dpp v24, v24, v24 row_mirror row_mask:0xf bank_mask:0xf
	v_mov_b32_e32 v25, v24
	s_nop 1
	v_permlane16_swap_b32_e32 v24, v25
	v_add_f32_e32 v24, v24, v25
	v_mov_b32_e32 v25, v24
	s_nop 1
	v_permlane32_swap_b32_e32 v24, v25
	v_add_f32_e32 v24, v24, v25
	v_fmamk_f32 v24, v24, 0x3b000000, v196
	v_mul_f32_e32 v25, 0x4b800000, v24
	v_cmp_gt_f32_e32 vcc, s35, v24
	s_nop 1
	v_cndmask_b32_e32 v24, v24, v25, vcc
	v_rsq_f32_e32 v24, v24
	s_nop 0
	v_mul_f32_e32 v25, 0x45800000, v24
	v_cndmask_b32_e32 v27, v24, v25, vcc
	v_mul_f32_e32 v24, v33, v27
	v_mul_f32_e32 v25, v35, v27
	v_mul_f32_e32 v24, v32, v24
	v_mul_f32_e32 v25, v34, v25
	v_cvt_pk_bf16_f32 v24, v24, v25
	v_mul_f32_e32 v25, v29, v27
	v_mul_f32_e32 v26, v41, v27
	v_mul_f32_e32 v25, v28, v25
	v_mul_f32_e32 v26, v40, v26
	v_cvt_pk_bf16_f32 v25, v25, v26
	v_mul_f32_e32 v26, v37, v27
	v_mul_f32_e32 v28, v43, v27
	v_mul_f32_e32 v26, v36, v26
	v_mul_f32_e32 v28, v42, v28
	v_cvt_pk_bf16_f32 v26, v26, v28
	v_mul_f32_e32 v28, v31, v27
	v_mul_f32_e32 v27, v39, v27
	v_mul_f32_e32 v28, v30, v28
	v_mul_f32_e32 v27, v38, v27
	v_cvt_pk_bf16_f32 v27, v28, v27
	v_lshl_add_u64 v[28:29], s[38:39], 0, v[122:123]
	v_lshlrev_b64 v[28:29], 11, v[28:29]
	v_lshl_add_u64 v[28:29], v[72:73], 0, v[28:29]
	global_store_dwordx4 v[28:29], v[24:27], off offset:1024
	s_and_b64 vcc, exec, s[0:1]
	s_mov_b64 s[0:1], 0
	s_cbranch_vccnz .LBB0_270
	s_bitcmp1_b32 s3, 3
	s_cbranch_scc0 .Lb_adv
	s_mov_b32 s98, 1
	s_branch .LBB0_255
